# attention K tile unpadded with XOR swizzle (conflict-free), QK sections regenerated: four independent accumulator chains with an 8-deep LDS read ring
# speedup vs baseline: 1.0227x; 1.0081x over previous
; #define LAS __attribute__((address_space(3)))
; __device__ __forceinline__ int opaque_tid() { int t = threadIdx.x; asm volatile("" : "+v"(t)); return t; }
; __device__ __forceinline__ void ph_attn(const Params& p, LAS unsigned char* lds) {
;     const int tid = opaque_tid(), lane = tid & 63, w = __builtin_amdgcn_readfirstlane(tid >> 6), fr = lane & 15, fq = lane >> 4;
;     unsigned char* ws = p.ws; const bf16_t* qb = (const bf16_t*)(ws + WS_A); const bf16_t* kb = (const bf16_t*)(ws + WS_KB); const bf16_t* vt = (const bf16_t*)(ws + WS_VT); bf16_t* ao = (bf16_t*)(ws + WS_B);
;     constexpr int PR = 36864;
;     LAS unsigned char* pw = lds + PR + w * 8448 + fr * 528 + fq * 8;
;     const unsigned koff = (unsigned)((tid >> 5) * 1024 + (tid & 31) * 8);
;     const unsigned voff = (unsigned)((tid >> 3) * 256 + (tid & 7) * 8);
;     LAS unsigned char* kst = lds + (tid >> 5) * 528 + (tid & 31) * 16;
;     LAS unsigned char* vst = lds + (tid >> 3) * 144 + (tid & 7) * 16;
;     const LAS unsigned char* krd = lds + fr * 528 + fq * 16;
;     const LAS unsigned char* vrd = lds + fr * 144 + fq * 16;
.LBB0_1080:
	s_cmp_lt_i32 s94, 9
	s_cselect_b64 s[0:1], -1, 0
	s_and_b64 s[4:5], s[0:1], s[4:5]
	s_andn2_b64 vcc, exec, s[4:5]
	s_cbranch_vccnz .LBB0_1110
	v_mov_b32_e32 v0, v200
	s_cmpk_gt_i32 s2, 0x43f
	s_nop 0
	v_readfirstlane_b32 s4, v0
	s_cbranch_scc1 .LBB0_1110
	s_add_u32 s6, s92, 0x11680000
	s_addc_u32 s7, s93, 0
	s_add_u32 s3, s92, 0x19c80000
	s_addc_u32 s14, s93, 0
	s_add_u32 s15, s92, 0x1a880000
	s_addc_u32 s20, s93, 0
	s_add_u32 s8, s92, 0x15780000
	s_addc_u32 s9, s93, 0
	s_ashr_i32 s4, s4, 6
	s_waitcnt lgkmcnt(0)
	v_and_b32_e32 v1, 15, v0
	s_waitcnt vmcnt(0)
	v_bfe_u32 v3, v0, 4, 2
	s_mul_i32 s5, s4, 0x2100
	v_ashrrev_i32_e32 v4, 5, v0
	v_and_b32_e32 v6, 31, v0
	v_ashrrev_i32_e32 v7, 3, v0
	v_and_b32_e32 v0, 7, v0
	s_add_i32 s10, s5, 0
	v_lshlrev_b32_e32 v11, 4, v0
	v_lshlrev_b32_e32 v0, 3, v0
	s_movk_i32 s12, 0x210
	v_mov_b32_e32 v2, s10
	s_movk_i32 s10, 0x90
	v_lshl_or_b32 v180, v7, 8, v0
	v_lshlrev_b32_e32 v0, 3, v6
	v_mad_u32_u24 v5, v1, s12, v2
	v_lshlrev_b32_e32 v2, 3, v3
	v_mul_lo_u32 v8, v4, s12
	v_mul_lo_u32 v10, v7, s10
	v_mad_u32_u24 v12, v1, s12, 0
	v_lshlrev_b32_e32 v13, 4, v3
	s_movk_i32 s10, 0xfe80
	v_lshl_or_b32 v182, v4, 10, v0
	s_lshl_b32 s21, s4, 4
	v_lshlrev_b32_e32 v4, 2, v3
	v_mov_b32_e32 v3, s5
	v_add_u32_e32 v193, v12, v13
	v_mad_i32_i24 v12, v1, s10, v12
	v_or_b32_e32 v196, s21, v1
	v_mad_u32_u24 v1, v1, s12, v3
	v_mov_b32_e32 v0, 0
	v_add3_u32 v1, v1, v13, 0
	v_add_u32_e32 v8, 0, v8
	v_lshlrev_b32_e32 v9, 4, v6
	v_add_u32_e32 v10, 0, v10
	v_mov_b32_e32 v181, v0
	v_add_u32_e32 v197, 0x9000, v1
	v_mbcnt_lo_u32_b32 v1, -1, 0
	s_mov_b32 s11, 0
	v_mov_b32_e32 v183, v0
	v_lshl_add_u64 v[184:185], v[180:181], 1, s[92:93]
	s_mov_b32 s22, 0x8000
	v_lshlrev_b32_e32 v186, 1, v2
	s_mov_b32 s23, 0x10000
	s_mov_b32 s24, 0x18000
	s_mov_b32 s25, 0x20000
	s_mov_b32 s26, 0xff61b1e6
	v_add_u32_e32 v198, v5, v2
	v_add_u32_e32 v199, v10, v11
	v_add_u32_e32 v201, v12, v13
	v_lshlrev_b32_e32 v188, 1, v4
	v_add_u32_e32 v202, v8, v9
	v_mbcnt_hi_u32_b32 v203, -1, v1
	s_mov_b32 s27, s2
	v_lshrrev_b32_e32 v237, 3, v200
	v_and_b32_e32 v238, 7, v200
	v_bfe_u32 v239, v200, 4, 3
	v_xor_b32_e32 v238, v238, v239
	v_lshlrev_b32_e32 v238, 4, v238
	v_lshl_add_u32 v199, v237, 7, v238
	v_and_b32_e32 v237, 15, v200
	v_bfe_u32 v238, v200, 4, 2
	v_bfe_u32 v239, v200, 1, 3
	v_xor_b32_e32 v238, v238, v239
	v_lshlrev_b32_e32 v238, 4, v238
	v_lshl_add_u32 v201, v237, 7, v238
	v_xor_b32_e32 v239, 64, v201
	v_lshrrev_b32_e32 v237, 5, v200
	v_and_b32_e32 v238, 31, v200
	v_xor_b32_e32 v238, v238, v237
	v_lshlrev_b32_e32 v238, 4, v238
	v_lshl_add_u32 v202, v237, 9, v238
	v_and_b32_e32 v237, 15, v200
	v_bfe_u32 v238, v200, 4, 2
	v_and_b32_e32 v193, 3, v237
	v_xor_b32_e32 v238, v238, v193
	v_lshlrev_b32_e32 v238, 4, v238
	v_lshrrev_b32_e32 v193, 2, v237
	v_lshl_add_u32 v238, v193, 6, v238
	v_lshl_add_u32 v193, v237, 9, v238
	s_branch .LBB0_1084

; #define LAS __attribute__((address_space(3)))
; #define LOADK(i) do { _Pragma("unroll") for (int j = 0; j < 4; ++j) st[j] = *(const u32x4*)(kbase + ((i) * 64 + j * 16) * 1024 + koff); } while (0)
; #define LOADV(i) do { _Pragma("unroll") for (int j = 0; j < 4; ++j) st[j] = *(const u32x4*)(vbase + (j * 64 * 256 + (i) * 64) + voff); } while (0)
; #define STOREK() do { _Pragma("unroll") for (int j = 0; j < 4; ++j) *(LAS u32x4*)(kst + j * 16 * 528) = st[j]; } while (0)
; __device__ __forceinline__ void ph_attn(const Params& p, LAS unsigned char* lds) {
;     ...
;         const bf16_t* kbase = kb + (size_t)kvb * 256 * 1024 + h * 256; const bf16_t* vbase = vt + ((size_t)kvb * 1024 + h * 256) * 256;
;     ...
;         f32x4 sc[16];
;         LOADK(0);
; #pragma unroll
;         for (int i = 0; i < 4; ++i) {
;             __syncthreads(); STOREK(); __syncthreads();
;             if (i < 3) LOADK(i + 1); else LOADV(0);
;             if (active) {
; #pragma unroll
;                 for (int sub = 0; sub < 4; ++sub) {
;                     f32x4 a = {0.f, 0.f, 0.f, 0.f};
; #pragma unroll
;                     for (int ks = 0; ks < 8; ++ks) {
;                         const bf16x8 kf = *(const LAS bf16x8*)(krd + sub * 16 * 528 + ks * 64);
;                         a = __builtin_amdgcn_mfma_f32_16x16x32_bf16(kf, qf[ks], a, 0, 0, 0);
;                     }
;                     sc[i * 4 + sub] = a;
;                 }
.LBB0_1092:
	s_ashr_i32 s5, s4, 31
	s_lshl_b64 s[16:17], s[4:5], 19
	s_add_u32 s18, s3, s16
	s_addc_u32 s19, s14, s17
	s_lshl_b64 s[4:5], s[10:11], 1
	s_add_u32 s98, s18, s4
	s_addc_u32 s99, s19, s5
	s_lshl_b64 s[18:19], s[10:11], 9
	s_add_u32 s100, s15, s16
	s_addc_u32 s101, s20, s17
	s_add_u32 s100, s100, s18
	s_addc_u32 s101, s101, s19
	v_lshlrev_b32_e32 v237, 1, v182
	v_lshlrev_b32_e32 v238, 1, v180
	v_xor_b32_e32 v124, 64, v193
	v_xor_b32_e32 v125, 0x80, v193
	v_xor_b32_e32 v126, 0xc0, v193
	v_mov_b32_e32 v100, v237
	v_add_u32_e32 v104, 0x8000, v237
	v_add_u32_e32 v108, 0x10000, v237
	v_add_u32_e32 v112, 0x18000, v237
	global_load_dwordx4 v[100:103], v100, s[98:99]
	global_load_dwordx4 v[104:107], v104, s[98:99]
	global_load_dwordx4 v[108:111], v108, s[98:99]
	global_load_dwordx4 v[112:115], v112, s[98:99]
	v_add_u32_e32 v240, 0x20000, v237
	v_add_u32_e32 v244, 0x28000, v237
	v_add_u32_e32 v248, 0x30000, v237
	v_add_u32_e32 v252, 0x38000, v237
	global_load_dwordx4 v[240:243], v240, s[98:99]
	global_load_dwordx4 v[244:247], v244, s[98:99]
	global_load_dwordx4 v[248:251], v248, s[98:99]
	global_load_dwordx4 v[252:255], v252, s[98:99]
	s_barrier
	s_waitcnt vmcnt(7)
	ds_write_b128 v202, v[100:103]
	s_waitcnt vmcnt(6)
	ds_write_b128 v202, v[104:107] offset:8192
	s_waitcnt vmcnt(5)
	ds_write_b128 v202, v[108:111] offset:16384
	s_waitcnt vmcnt(4)
	ds_write_b128 v202, v[112:115] offset:24576
	v_add_u32_e32 v100, 0x40000, v237
	v_add_u32_e32 v104, 0x48000, v237
	v_add_u32_e32 v108, 0x50000, v237
	v_add_u32_e32 v112, 0x58000, v237
	s_waitcnt lgkmcnt(0)
	s_barrier
	global_load_dwordx4 v[100:103], v100, s[98:99]
	global_load_dwordx4 v[104:107], v104, s[98:99]
	global_load_dwordx4 v[108:111], v108, s[98:99]
	global_load_dwordx4 v[112:115], v112, s[98:99]
	s_and_b64 vcc, exec, s[12:13]
	s_cbranch_vccz .LBB0_1094
	ds_read_b128 v[128:131], v193
	ds_read_b128 v[132:135], v193 offset:8192
	ds_read_b128 v[136:139], v193 offset:16384
	ds_read_b128 v[140:143], v193 offset:24576
	ds_read_b128 v[144:147], v124
	ds_read_b128 v[148:151], v124 offset:8192
	ds_read_b128 v[152:155], v124 offset:16384
	ds_read_b128 v[156:159], v124 offset:24576
	s_waitcnt lgkmcnt(7)
	v_mfma_f32_16x16x32_bf16 v[48:51], v[128:131], v[32:35], 0
	ds_read_b128 v[160:163], v125
	s_waitcnt lgkmcnt(7)
	v_mfma_f32_16x16x32_bf16 v[64:67], v[132:135], v[32:35], 0
	ds_read_b128 v[164:167], v125 offset:8192
	s_waitcnt lgkmcnt(7)
	v_mfma_f32_16x16x32_bf16 v[80:83], v[136:139], v[32:35], 0
	ds_read_b128 v[168:171], v125 offset:16384
	s_waitcnt lgkmcnt(7)
	v_mfma_f32_16x16x32_bf16 v[96:99], v[140:143], v[32:35], 0
	ds_read_b128 v[172:175], v125 offset:24576
	s_waitcnt lgkmcnt(7)
	v_mfma_f32_16x16x32_bf16 v[48:51], v[144:147], v[28:31], v[48:51]
	ds_read_b128 v[176:179], v126
	s_waitcnt lgkmcnt(7)
	v_mfma_f32_16x16x32_bf16 v[64:67], v[148:151], v[28:31], v[64:67]
	ds_read_b128 v[128:131], v126 offset:8192
	s_waitcnt lgkmcnt(7)
	v_mfma_f32_16x16x32_bf16 v[80:83], v[152:155], v[28:31], v[80:83]
	ds_read_b128 v[132:135], v126 offset:16384
	s_waitcnt lgkmcnt(7)
	v_mfma_f32_16x16x32_bf16 v[96:99], v[156:159], v[28:31], v[96:99]
	ds_read_b128 v[136:139], v126 offset:24576
	s_waitcnt lgkmcnt(7)
	v_mfma_f32_16x16x32_bf16 v[48:51], v[160:163], v[24:27], v[48:51]
	ds_read_b128 v[140:143], v193 offset:256
	s_waitcnt lgkmcnt(7)
	v_mfma_f32_16x16x32_bf16 v[64:67], v[164:167], v[24:27], v[64:67]
	ds_read_b128 v[144:147], v193 offset:8448
	s_waitcnt lgkmcnt(7)
	v_mfma_f32_16x16x32_bf16 v[80:83], v[168:171], v[24:27], v[80:83]
	ds_read_b128 v[148:151], v193 offset:16640
	s_waitcnt lgkmcnt(7)
	v_mfma_f32_16x16x32_bf16 v[96:99], v[172:175], v[24:27], v[96:99]
	ds_read_b128 v[152:155], v193 offset:24832
	s_waitcnt lgkmcnt(7)
	v_mfma_f32_16x16x32_bf16 v[48:51], v[176:179], v[20:23], v[48:51]
	ds_read_b128 v[156:159], v124 offset:256
	s_waitcnt lgkmcnt(7)
	v_mfma_f32_16x16x32_bf16 v[64:67], v[128:131], v[20:23], v[64:67]
	ds_read_b128 v[160:163], v124 offset:8448
	s_waitcnt lgkmcnt(7)
	v_mfma_f32_16x16x32_bf16 v[80:83], v[132:135], v[20:23], v[80:83]
	ds_read_b128 v[164:167], v124 offset:16640
	s_waitcnt lgkmcnt(7)
	v_mfma_f32_16x16x32_bf16 v[96:99], v[136:139], v[20:23], v[96:99]
	ds_read_b128 v[168:171], v124 offset:24832
	s_waitcnt lgkmcnt(7)
	v_mfma_f32_16x16x32_bf16 v[48:51], v[140:143], v[16:19], v[48:51]
	ds_read_b128 v[172:175], v125 offset:256
	s_waitcnt lgkmcnt(7)
	v_mfma_f32_16x16x32_bf16 v[64:67], v[144:147], v[16:19], v[64:67]
	ds_read_b128 v[176:179], v125 offset:8448
	s_waitcnt lgkmcnt(7)
	v_mfma_f32_16x16x32_bf16 v[80:83], v[148:151], v[16:19], v[80:83]
	ds_read_b128 v[128:131], v125 offset:16640
	s_waitcnt lgkmcnt(7)
	v_mfma_f32_16x16x32_bf16 v[96:99], v[152:155], v[16:19], v[96:99]
	ds_read_b128 v[132:135], v125 offset:24832
	s_waitcnt lgkmcnt(7)
	v_mfma_f32_16x16x32_bf16 v[48:51], v[156:159], v[12:15], v[48:51]
	ds_read_b128 v[136:139], v126 offset:256
	s_waitcnt lgkmcnt(7)
	v_mfma_f32_16x16x32_bf16 v[64:67], v[160:163], v[12:15], v[64:67]
	ds_read_b128 v[140:143], v126 offset:8448
	s_waitcnt lgkmcnt(7)
	v_mfma_f32_16x16x32_bf16 v[80:83], v[164:167], v[12:15], v[80:83]
	ds_read_b128 v[144:147], v126 offset:16640
	s_waitcnt lgkmcnt(7)
	v_mfma_f32_16x16x32_bf16 v[96:99], v[168:171], v[12:15], v[96:99]
	ds_read_b128 v[148:151], v126 offset:24832
	s_waitcnt lgkmcnt(7)
	v_mfma_f32_16x16x32_bf16 v[48:51], v[172:175], v[8:11], v[48:51]
	s_waitcnt lgkmcnt(6)
	v_mfma_f32_16x16x32_bf16 v[64:67], v[176:179], v[8:11], v[64:67]
	s_waitcnt lgkmcnt(5)
	v_mfma_f32_16x16x32_bf16 v[80:83], v[128:131], v[8:11], v[80:83]
	s_waitcnt lgkmcnt(4)
	v_mfma_f32_16x16x32_bf16 v[96:99], v[132:135], v[8:11], v[96:99]
	s_waitcnt lgkmcnt(3)
	v_mfma_f32_16x16x32_bf16 v[48:51], v[136:139], v[4:7], v[48:51]
	s_waitcnt lgkmcnt(2)
	v_mfma_f32_16x16x32_bf16 v[64:67], v[140:143], v[4:7], v[64:67]
	s_waitcnt lgkmcnt(1)
	v_mfma_f32_16x16x32_bf16 v[80:83], v[144:147], v[4:7], v[80:83]
	s_waitcnt lgkmcnt(0)
	v_mfma_f32_16x16x32_bf16 v[96:99], v[148:151], v[4:7], v[96:99]
; #define LAS __attribute__((address_space(3)))
; #define LOADK(i) do { _Pragma("unroll") for (int j = 0; j < 4; ++j) st[j] = *(const u32x4*)(kbase + ((i) * 64 + j * 16) * 1024 + koff); } while (0)
; #define LOADV(i) do { _Pragma("unroll") for (int j = 0; j < 4; ++j) st[j] = *(const u32x4*)(vbase + (j * 64 * 256 + (i) * 64) + voff); } while (0)
; #define STOREK() do { _Pragma("unroll") for (int j = 0; j < 4; ++j) *(LAS u32x4*)(kst + j * 16 * 528) = st[j]; } while (0)
; __device__ __forceinline__ void ph_attn(const Params& p, LAS unsigned char* lds) {
;     ...
;         f32x4 sc[16];
;         LOADK(0);
; #pragma unroll
;         for (int i = 0; i < 4; ++i) {
;             __syncthreads(); STOREK(); __syncthreads();
;             if (i < 3) LOADK(i + 1); else LOADV(0);
;             if (active) {
; #pragma unroll
;                 for (int sub = 0; sub < 4; ++sub) {
;                     f32x4 a = {0.f, 0.f, 0.f, 0.f};
; #pragma unroll
;                     for (int ks = 0; ks < 8; ++ks) {
;                         const bf16x8 kf = *(const LAS bf16x8*)(krd + sub * 16 * 528 + ks * 64);
;                         a = __builtin_amdgcn_mfma_f32_16x16x32_bf16(kf, qf[ks], a, 0, 0, 0);
;                     }
;                     sc[i * 4 + sub] = a;
;                 }
.LBB0_1094:
	s_barrier
	s_waitcnt vmcnt(7)
	ds_write_b128 v202, v[240:243]
	s_waitcnt vmcnt(6)
	ds_write_b128 v202, v[244:247] offset:8192
	s_waitcnt vmcnt(5)
	ds_write_b128 v202, v[248:251] offset:16384
	s_waitcnt vmcnt(4)
	ds_write_b128 v202, v[252:255] offset:24576
	v_add_u32_e32 v240, 0x60000, v237
	v_add_u32_e32 v244, 0x68000, v237
	v_add_u32_e32 v248, 0x70000, v237
	v_add_u32_e32 v252, 0x78000, v237
	s_waitcnt lgkmcnt(0)
	s_barrier
	global_load_dwordx4 v[240:243], v240, s[98:99]
	global_load_dwordx4 v[244:247], v244, s[98:99]
	global_load_dwordx4 v[248:251], v248, s[98:99]
	global_load_dwordx4 v[252:255], v252, s[98:99]
	v_cndmask_b32_e64 v1, 0, 1, s[12:13]
	v_cmp_ne_u32_e64 s[4:5], 1, v1
	s_andn2_b64 vcc, exec, s[12:13]
	s_cbranch_vccnz .LBB0_1096
	ds_read_b128 v[128:131], v193
	ds_read_b128 v[132:135], v193 offset:8192
	ds_read_b128 v[136:139], v193 offset:16384
	ds_read_b128 v[140:143], v193 offset:24576
	ds_read_b128 v[144:147], v124
	ds_read_b128 v[148:151], v124 offset:8192
	ds_read_b128 v[152:155], v124 offset:16384
	ds_read_b128 v[156:159], v124 offset:24576
	s_waitcnt lgkmcnt(7)
	v_mfma_f32_16x16x32_bf16 v[44:47], v[128:131], v[32:35], 0
	ds_read_b128 v[160:163], v125
	s_waitcnt lgkmcnt(7)
	v_mfma_f32_16x16x32_bf16 v[60:63], v[132:135], v[32:35], 0
	ds_read_b128 v[164:167], v125 offset:8192
	s_waitcnt lgkmcnt(7)
	v_mfma_f32_16x16x32_bf16 v[76:79], v[136:139], v[32:35], 0
	ds_read_b128 v[168:171], v125 offset:16384
	s_waitcnt lgkmcnt(7)
	v_mfma_f32_16x16x32_bf16 v[92:95], v[140:143], v[32:35], 0
	ds_read_b128 v[172:175], v125 offset:24576
	s_waitcnt lgkmcnt(7)
	v_mfma_f32_16x16x32_bf16 v[44:47], v[144:147], v[28:31], v[44:47]
	ds_read_b128 v[176:179], v126
	s_waitcnt lgkmcnt(7)
	v_mfma_f32_16x16x32_bf16 v[60:63], v[148:151], v[28:31], v[60:63]
	ds_read_b128 v[128:131], v126 offset:8192
	s_waitcnt lgkmcnt(7)
	v_mfma_f32_16x16x32_bf16 v[76:79], v[152:155], v[28:31], v[76:79]
	ds_read_b128 v[132:135], v126 offset:16384
	s_waitcnt lgkmcnt(7)
	v_mfma_f32_16x16x32_bf16 v[92:95], v[156:159], v[28:31], v[92:95]
	ds_read_b128 v[136:139], v126 offset:24576
	s_waitcnt lgkmcnt(7)
	v_mfma_f32_16x16x32_bf16 v[44:47], v[160:163], v[24:27], v[44:47]
	ds_read_b128 v[140:143], v193 offset:256
	s_waitcnt lgkmcnt(7)
	v_mfma_f32_16x16x32_bf16 v[60:63], v[164:167], v[24:27], v[60:63]
	ds_read_b128 v[144:147], v193 offset:8448
	s_waitcnt lgkmcnt(7)
	v_mfma_f32_16x16x32_bf16 v[76:79], v[168:171], v[24:27], v[76:79]
	ds_read_b128 v[148:151], v193 offset:16640
	s_waitcnt lgkmcnt(7)
	v_mfma_f32_16x16x32_bf16 v[92:95], v[172:175], v[24:27], v[92:95]
	ds_read_b128 v[152:155], v193 offset:24832
	s_waitcnt lgkmcnt(7)
	v_mfma_f32_16x16x32_bf16 v[44:47], v[176:179], v[20:23], v[44:47]
	ds_read_b128 v[156:159], v124 offset:256
	s_waitcnt lgkmcnt(7)
	v_mfma_f32_16x16x32_bf16 v[60:63], v[128:131], v[20:23], v[60:63]
	ds_read_b128 v[160:163], v124 offset:8448
	s_waitcnt lgkmcnt(7)
	v_mfma_f32_16x16x32_bf16 v[76:79], v[132:135], v[20:23], v[76:79]
	ds_read_b128 v[164:167], v124 offset:16640
	s_waitcnt lgkmcnt(7)
	v_mfma_f32_16x16x32_bf16 v[92:95], v[136:139], v[20:23], v[92:95]
	ds_read_b128 v[168:171], v124 offset:24832
	s_waitcnt lgkmcnt(7)
	v_mfma_f32_16x16x32_bf16 v[44:47], v[140:143], v[16:19], v[44:47]
	ds_read_b128 v[172:175], v125 offset:256
	s_waitcnt lgkmcnt(7)
	v_mfma_f32_16x16x32_bf16 v[60:63], v[144:147], v[16:19], v[60:63]
	ds_read_b128 v[176:179], v125 offset:8448
	s_waitcnt lgkmcnt(7)
	v_mfma_f32_16x16x32_bf16 v[76:79], v[148:151], v[16:19], v[76:79]
	ds_read_b128 v[128:131], v125 offset:16640
	s_waitcnt lgkmcnt(7)
	v_mfma_f32_16x16x32_bf16 v[92:95], v[152:155], v[16:19], v[92:95]
	ds_read_b128 v[132:135], v125 offset:24832
	s_waitcnt lgkmcnt(7)
	v_mfma_f32_16x16x32_bf16 v[44:47], v[156:159], v[12:15], v[44:47]
	ds_read_b128 v[136:139], v126 offset:256
	s_waitcnt lgkmcnt(7)
	v_mfma_f32_16x16x32_bf16 v[60:63], v[160:163], v[12:15], v[60:63]
	ds_read_b128 v[140:143], v126 offset:8448
	s_waitcnt lgkmcnt(7)
	v_mfma_f32_16x16x32_bf16 v[76:79], v[164:167], v[12:15], v[76:79]
	ds_read_b128 v[144:147], v126 offset:16640
	s_waitcnt lgkmcnt(7)
	v_mfma_f32_16x16x32_bf16 v[92:95], v[168:171], v[12:15], v[92:95]
	ds_read_b128 v[148:151], v126 offset:24832
	s_waitcnt lgkmcnt(7)
	v_mfma_f32_16x16x32_bf16 v[44:47], v[172:175], v[8:11], v[44:47]
	s_waitcnt lgkmcnt(6)
	v_mfma_f32_16x16x32_bf16 v[60:63], v[176:179], v[8:11], v[60:63]
	s_waitcnt lgkmcnt(5)
	v_mfma_f32_16x16x32_bf16 v[76:79], v[128:131], v[8:11], v[76:79]
	s_waitcnt lgkmcnt(4)
	v_mfma_f32_16x16x32_bf16 v[92:95], v[132:135], v[8:11], v[92:95]
	s_waitcnt lgkmcnt(3)
	v_mfma_f32_16x16x32_bf16 v[44:47], v[136:139], v[4:7], v[44:47]
	s_waitcnt lgkmcnt(2)
	v_mfma_f32_16x16x32_bf16 v[60:63], v[140:143], v[4:7], v[60:63]
	s_waitcnt lgkmcnt(1)
	v_mfma_f32_16x16x32_bf16 v[76:79], v[144:147], v[4:7], v[76:79]
	s_waitcnt lgkmcnt(0)
	v_mfma_f32_16x16x32_bf16 v[92:95], v[148:151], v[4:7], v[92:95]
; #define LAS __attribute__((address_space(3)))
; #define LOADK(i) do { _Pragma("unroll") for (int j = 0; j < 4; ++j) st[j] = *(const u32x4*)(kbase + ((i) * 64 + j * 16) * 1024 + koff); } while (0)
; #define LOADV(i) do { _Pragma("unroll") for (int j = 0; j < 4; ++j) st[j] = *(const u32x4*)(vbase + (j * 64 * 256 + (i) * 64) + voff); } while (0)
; #define STOREK() do { _Pragma("unroll") for (int j = 0; j < 4; ++j) *(LAS u32x4*)(kst + j * 16 * 528) = st[j]; } while (0)
; __device__ __forceinline__ void ph_attn(const Params& p, LAS unsigned char* lds) {
;     ...
;         f32x4 sc[16];
;         LOADK(0);
; #pragma unroll
;         for (int i = 0; i < 4; ++i) {
;             __syncthreads(); STOREK(); __syncthreads();
;             if (i < 3) LOADK(i + 1); else LOADV(0);
;             if (active) {
; #pragma unroll
;                 for (int sub = 0; sub < 4; ++sub) {
;                     f32x4 a = {0.f, 0.f, 0.f, 0.f};
; #pragma unroll
;                     for (int ks = 0; ks < 8; ++ks) {
;                         const bf16x8 kf = *(const LAS bf16x8*)(krd + sub * 16 * 528 + ks * 64);
;                         a = __builtin_amdgcn_mfma_f32_16x16x32_bf16(kf, qf[ks], a, 0, 0, 0);
;                     }
;                     sc[i * 4 + sub] = a;
;                 }
.LBB0_1096:
	s_barrier
	s_waitcnt vmcnt(7)
	ds_write_b128 v202, v[100:103]
	s_waitcnt vmcnt(6)
	ds_write_b128 v202, v[104:107] offset:8192
	s_waitcnt vmcnt(5)
	ds_write_b128 v202, v[108:111] offset:16384
	s_waitcnt vmcnt(4)
	ds_write_b128 v202, v[112:115] offset:24576
	v_mov_b32_e32 v100, v238
	v_add_u32_e32 v104, 0x8000, v238
	v_add_u32_e32 v108, 0x10000, v238
	v_add_u32_e32 v112, 0x18000, v238
	s_waitcnt lgkmcnt(0)
	s_barrier
	global_load_dwordx4 v[100:103], v100, s[100:101]
	global_load_dwordx4 v[104:107], v104, s[100:101]
	global_load_dwordx4 v[108:111], v108, s[100:101]
	global_load_dwordx4 v[112:115], v112, s[100:101]
	s_and_b64 vcc, exec, s[4:5]
	s_cbranch_vccnz .LBB0_1098
	ds_read_b128 v[128:131], v193
	ds_read_b128 v[132:135], v193 offset:8192
	ds_read_b128 v[136:139], v193 offset:16384
	ds_read_b128 v[140:143], v193 offset:24576
	ds_read_b128 v[144:147], v124
	ds_read_b128 v[148:151], v124 offset:8192
	ds_read_b128 v[152:155], v124 offset:16384
	ds_read_b128 v[156:159], v124 offset:24576
	s_waitcnt lgkmcnt(7)
	v_mfma_f32_16x16x32_bf16 v[40:43], v[128:131], v[32:35], 0
	ds_read_b128 v[160:163], v125
	s_waitcnt lgkmcnt(7)
	v_mfma_f32_16x16x32_bf16 v[56:59], v[132:135], v[32:35], 0
	ds_read_b128 v[164:167], v125 offset:8192
	s_waitcnt lgkmcnt(7)
	v_mfma_f32_16x16x32_bf16 v[72:75], v[136:139], v[32:35], 0
	ds_read_b128 v[168:171], v125 offset:16384
	s_waitcnt lgkmcnt(7)
	v_mfma_f32_16x16x32_bf16 v[88:91], v[140:143], v[32:35], 0
	ds_read_b128 v[172:175], v125 offset:24576
	s_waitcnt lgkmcnt(7)
	v_mfma_f32_16x16x32_bf16 v[40:43], v[144:147], v[28:31], v[40:43]
	ds_read_b128 v[176:179], v126
	s_waitcnt lgkmcnt(7)
	v_mfma_f32_16x16x32_bf16 v[56:59], v[148:151], v[28:31], v[56:59]
	ds_read_b128 v[128:131], v126 offset:8192
	s_waitcnt lgkmcnt(7)
	v_mfma_f32_16x16x32_bf16 v[72:75], v[152:155], v[28:31], v[72:75]
	ds_read_b128 v[132:135], v126 offset:16384
	s_waitcnt lgkmcnt(7)
	v_mfma_f32_16x16x32_bf16 v[88:91], v[156:159], v[28:31], v[88:91]
	ds_read_b128 v[136:139], v126 offset:24576
	s_waitcnt lgkmcnt(7)
	v_mfma_f32_16x16x32_bf16 v[40:43], v[160:163], v[24:27], v[40:43]
	ds_read_b128 v[140:143], v193 offset:256
	s_waitcnt lgkmcnt(7)
	v_mfma_f32_16x16x32_bf16 v[56:59], v[164:167], v[24:27], v[56:59]
	ds_read_b128 v[144:147], v193 offset:8448
	s_waitcnt lgkmcnt(7)
	v_mfma_f32_16x16x32_bf16 v[72:75], v[168:171], v[24:27], v[72:75]
	ds_read_b128 v[148:151], v193 offset:16640
	s_waitcnt lgkmcnt(7)
	v_mfma_f32_16x16x32_bf16 v[88:91], v[172:175], v[24:27], v[88:91]
	ds_read_b128 v[152:155], v193 offset:24832
	s_waitcnt lgkmcnt(7)
	v_mfma_f32_16x16x32_bf16 v[40:43], v[176:179], v[20:23], v[40:43]
	ds_read_b128 v[156:159], v124 offset:256
	s_waitcnt lgkmcnt(7)
	v_mfma_f32_16x16x32_bf16 v[56:59], v[128:131], v[20:23], v[56:59]
	ds_read_b128 v[160:163], v124 offset:8448
	s_waitcnt lgkmcnt(7)
	v_mfma_f32_16x16x32_bf16 v[72:75], v[132:135], v[20:23], v[72:75]
	ds_read_b128 v[164:167], v124 offset:16640
	s_waitcnt lgkmcnt(7)
	v_mfma_f32_16x16x32_bf16 v[88:91], v[136:139], v[20:23], v[88:91]
	ds_read_b128 v[168:171], v124 offset:24832
	s_waitcnt lgkmcnt(7)
	v_mfma_f32_16x16x32_bf16 v[40:43], v[140:143], v[16:19], v[40:43]
	ds_read_b128 v[172:175], v125 offset:256
	s_waitcnt lgkmcnt(7)
	v_mfma_f32_16x16x32_bf16 v[56:59], v[144:147], v[16:19], v[56:59]
	ds_read_b128 v[176:179], v125 offset:8448
	s_waitcnt lgkmcnt(7)
	v_mfma_f32_16x16x32_bf16 v[72:75], v[148:151], v[16:19], v[72:75]
	ds_read_b128 v[128:131], v125 offset:16640
	s_waitcnt lgkmcnt(7)
	v_mfma_f32_16x16x32_bf16 v[88:91], v[152:155], v[16:19], v[88:91]
	ds_read_b128 v[132:135], v125 offset:24832
	s_waitcnt lgkmcnt(7)
	v_mfma_f32_16x16x32_bf16 v[40:43], v[156:159], v[12:15], v[40:43]
	ds_read_b128 v[136:139], v126 offset:256
	s_waitcnt lgkmcnt(7)
	v_mfma_f32_16x16x32_bf16 v[56:59], v[160:163], v[12:15], v[56:59]
	ds_read_b128 v[140:143], v126 offset:8448
	s_waitcnt lgkmcnt(7)
	v_mfma_f32_16x16x32_bf16 v[72:75], v[164:167], v[12:15], v[72:75]
	ds_read_b128 v[144:147], v126 offset:16640
	s_waitcnt lgkmcnt(7)
	v_mfma_f32_16x16x32_bf16 v[88:91], v[168:171], v[12:15], v[88:91]
	ds_read_b128 v[148:151], v126 offset:24832
	s_waitcnt lgkmcnt(7)
	v_mfma_f32_16x16x32_bf16 v[40:43], v[172:175], v[8:11], v[40:43]
	s_waitcnt lgkmcnt(6)
	v_mfma_f32_16x16x32_bf16 v[56:59], v[176:179], v[8:11], v[56:59]
	s_waitcnt lgkmcnt(5)
	v_mfma_f32_16x16x32_bf16 v[72:75], v[128:131], v[8:11], v[72:75]
	s_waitcnt lgkmcnt(4)
	v_mfma_f32_16x16x32_bf16 v[88:91], v[132:135], v[8:11], v[88:91]
	s_waitcnt lgkmcnt(3)
	v_mfma_f32_16x16x32_bf16 v[40:43], v[136:139], v[4:7], v[40:43]
	s_waitcnt lgkmcnt(2)
	v_mfma_f32_16x16x32_bf16 v[56:59], v[140:143], v[4:7], v[56:59]
	s_waitcnt lgkmcnt(1)
	v_mfma_f32_16x16x32_bf16 v[72:75], v[144:147], v[4:7], v[72:75]
	s_waitcnt lgkmcnt(0)
	v_mfma_f32_16x16x32_bf16 v[88:91], v[148:151], v[4:7], v[88:91]
; #define LAS __attribute__((address_space(3)))
; #define LOADK(i) do { _Pragma("unroll") for (int j = 0; j < 4; ++j) st[j] = *(const u32x4*)(kbase + ((i) * 64 + j * 16) * 1024 + koff); } while (0)
; #define LOADV(i) do { _Pragma("unroll") for (int j = 0; j < 4; ++j) st[j] = *(const u32x4*)(vbase + (j * 64 * 256 + (i) * 64) + voff); } while (0)
; #define STOREK() do { _Pragma("unroll") for (int j = 0; j < 4; ++j) *(LAS u32x4*)(kst + j * 16 * 528) = st[j]; } while (0)
; __device__ __forceinline__ void ph_attn(const Params& p, LAS unsigned char* lds) {
;     ...
;         f32x4 sc[16];
;         LOADK(0);
; #pragma unroll
;         for (int i = 0; i < 4; ++i) {
;             __syncthreads(); STOREK(); __syncthreads();
;             if (i < 3) LOADK(i + 1); else LOADV(0);
;             if (active) {
; #pragma unroll
;                 for (int sub = 0; sub < 4; ++sub) {
;                     f32x4 a = {0.f, 0.f, 0.f, 0.f};
; #pragma unroll
;                     for (int ks = 0; ks < 8; ++ks) {
;                         const bf16x8 kf = *(const LAS bf16x8*)(krd + sub * 16 * 528 + ks * 64);
;                         a = __builtin_amdgcn_mfma_f32_16x16x32_bf16(kf, qf[ks], a, 0, 0, 0);
;                     }
;                     sc[i * 4 + sub] = a;
;                 }
.LBB0_1098:
	s_lshl_b64 s[18:19], s[10:11], 9
	s_add_u32 s28, s15, s16
	s_addc_u32 s29, s20, s17
	s_add_u32 s28, s28, s18
	s_addc_u32 s29, s29, s19
	s_barrier
	s_waitcnt vmcnt(7)
	ds_write_b128 v202, v[240:243]
	s_waitcnt vmcnt(6)
	ds_write_b128 v202, v[244:247] offset:8192
	s_waitcnt vmcnt(5)
	ds_write_b128 v202, v[248:251] offset:16384
	s_waitcnt vmcnt(4)
	ds_write_b128 v202, v[252:255] offset:24576
	v_mov_b32_e32 v240, v238
	v_add_u32_e32 v244, 0x8000, v238
	v_add_u32_e32 v248, 0x10000, v238
	v_add_u32_e32 v252, 0x18000, v238
	s_waitcnt lgkmcnt(0)
	s_barrier
	global_load_dwordx4 v[240:243], v240, s[100:101] offset:128
	global_load_dwordx4 v[244:247], v244, s[100:101] offset:128
	global_load_dwordx4 v[248:251], v248, s[100:101] offset:128
	global_load_dwordx4 v[252:255], v252, s[100:101] offset:128
	s_and_b64 vcc, exec, s[4:5]
	s_cbranch_vccnz .LBB0_1100
	ds_read_b128 v[128:131], v193
	ds_read_b128 v[132:135], v193 offset:8192
	ds_read_b128 v[136:139], v193 offset:16384
	ds_read_b128 v[140:143], v193 offset:24576
	ds_read_b128 v[144:147], v124
	ds_read_b128 v[148:151], v124 offset:8192
	ds_read_b128 v[152:155], v124 offset:16384
	ds_read_b128 v[156:159], v124 offset:24576
	s_waitcnt lgkmcnt(7)
	v_mfma_f32_16x16x32_bf16 v[36:39], v[128:131], v[32:35], 0
	ds_read_b128 v[160:163], v125
	s_waitcnt lgkmcnt(7)
	v_mfma_f32_16x16x32_bf16 v[52:55], v[132:135], v[32:35], 0
	ds_read_b128 v[164:167], v125 offset:8192
	s_waitcnt lgkmcnt(7)
	v_mfma_f32_16x16x32_bf16 v[68:71], v[136:139], v[32:35], 0
	ds_read_b128 v[168:171], v125 offset:16384
	s_waitcnt lgkmcnt(7)
	v_mfma_f32_16x16x32_bf16 v[84:87], v[140:143], v[32:35], 0
	ds_read_b128 v[172:175], v125 offset:24576
	s_waitcnt lgkmcnt(7)
	v_mfma_f32_16x16x32_bf16 v[36:39], v[144:147], v[28:31], v[36:39]
	ds_read_b128 v[176:179], v126
	s_waitcnt lgkmcnt(7)
	v_mfma_f32_16x16x32_bf16 v[52:55], v[148:151], v[28:31], v[52:55]
	ds_read_b128 v[128:131], v126 offset:8192
	s_waitcnt lgkmcnt(7)
	v_mfma_f32_16x16x32_bf16 v[68:71], v[152:155], v[28:31], v[68:71]
	ds_read_b128 v[132:135], v126 offset:16384
	s_waitcnt lgkmcnt(7)
	v_mfma_f32_16x16x32_bf16 v[84:87], v[156:159], v[28:31], v[84:87]
	ds_read_b128 v[136:139], v126 offset:24576
	s_waitcnt lgkmcnt(7)
	v_mfma_f32_16x16x32_bf16 v[36:39], v[160:163], v[24:27], v[36:39]
	ds_read_b128 v[140:143], v193 offset:256
	s_waitcnt lgkmcnt(7)
	v_mfma_f32_16x16x32_bf16 v[52:55], v[164:167], v[24:27], v[52:55]
	ds_read_b128 v[144:147], v193 offset:8448
	s_waitcnt lgkmcnt(7)
	v_mfma_f32_16x16x32_bf16 v[68:71], v[168:171], v[24:27], v[68:71]
	ds_read_b128 v[148:151], v193 offset:16640
	s_waitcnt lgkmcnt(7)
	v_mfma_f32_16x16x32_bf16 v[84:87], v[172:175], v[24:27], v[84:87]
	ds_read_b128 v[152:155], v193 offset:24832
	s_waitcnt lgkmcnt(7)
	v_mfma_f32_16x16x32_bf16 v[36:39], v[176:179], v[20:23], v[36:39]
	ds_read_b128 v[156:159], v124 offset:256
	s_waitcnt lgkmcnt(7)
	v_mfma_f32_16x16x32_bf16 v[52:55], v[128:131], v[20:23], v[52:55]
	ds_read_b128 v[160:163], v124 offset:8448
	s_waitcnt lgkmcnt(7)
	v_mfma_f32_16x16x32_bf16 v[68:71], v[132:135], v[20:23], v[68:71]
	ds_read_b128 v[164:167], v124 offset:16640
	s_waitcnt lgkmcnt(7)
	v_mfma_f32_16x16x32_bf16 v[84:87], v[136:139], v[20:23], v[84:87]
	ds_read_b128 v[168:171], v124 offset:24832
	s_waitcnt lgkmcnt(7)
	v_mfma_f32_16x16x32_bf16 v[36:39], v[140:143], v[16:19], v[36:39]
	ds_read_b128 v[172:175], v125 offset:256
	s_waitcnt lgkmcnt(7)
	v_mfma_f32_16x16x32_bf16 v[52:55], v[144:147], v[16:19], v[52:55]
	ds_read_b128 v[176:179], v125 offset:8448
	s_waitcnt lgkmcnt(7)
	v_mfma_f32_16x16x32_bf16 v[68:71], v[148:151], v[16:19], v[68:71]
	ds_read_b128 v[128:131], v125 offset:16640
	s_waitcnt lgkmcnt(7)
	v_mfma_f32_16x16x32_bf16 v[84:87], v[152:155], v[16:19], v[84:87]
	ds_read_b128 v[132:135], v125 offset:24832
	s_waitcnt lgkmcnt(7)
	v_mfma_f32_16x16x32_bf16 v[36:39], v[156:159], v[12:15], v[36:39]
	ds_read_b128 v[136:139], v126 offset:256
	s_waitcnt lgkmcnt(7)
	v_mfma_f32_16x16x32_bf16 v[52:55], v[160:163], v[12:15], v[52:55]
	ds_read_b128 v[140:143], v126 offset:8448
	s_waitcnt lgkmcnt(7)
	v_mfma_f32_16x16x32_bf16 v[68:71], v[164:167], v[12:15], v[68:71]
	ds_read_b128 v[144:147], v126 offset:16640
	s_waitcnt lgkmcnt(7)
	v_mfma_f32_16x16x32_bf16 v[84:87], v[168:171], v[12:15], v[84:87]
	ds_read_b128 v[148:151], v126 offset:24832
	s_waitcnt lgkmcnt(7)
	v_mfma_f32_16x16x32_bf16 v[36:39], v[172:175], v[8:11], v[36:39]
	s_waitcnt lgkmcnt(6)
	v_mfma_f32_16x16x32_bf16 v[52:55], v[176:179], v[8:11], v[52:55]
	s_waitcnt lgkmcnt(5)
	v_mfma_f32_16x16x32_bf16 v[68:71], v[128:131], v[8:11], v[68:71]
	s_waitcnt lgkmcnt(4)
	v_mfma_f32_16x16x32_bf16 v[84:87], v[132:135], v[8:11], v[84:87]
	s_waitcnt lgkmcnt(3)
	v_mfma_f32_16x16x32_bf16 v[36:39], v[136:139], v[4:7], v[36:39]
	s_waitcnt lgkmcnt(2)
	v_mfma_f32_16x16x32_bf16 v[52:55], v[140:143], v[4:7], v[52:55]
	s_waitcnt lgkmcnt(1)
	v_mfma_f32_16x16x32_bf16 v[68:71], v[144:147], v[4:7], v[68:71]
	s_waitcnt lgkmcnt(0)
	v_mfma_f32_16x16x32_bf16 v[84:87], v[148:151], v[4:7], v[84:87]
